# conversion loop waits made independent of load-vs-store retirement order
# speedup vs baseline: 1.0400x; 1.0050x over previous
.LcvA_ld2_end:
	s_lshl_b32 s55, s55, 6
	s_lshl_b32 s59, s59, 6
	s_mul_i32 s58, s59, s50
	s_lshl_b32 s61, s55, 2
	s_add_u32 s58, s58, s61
	s_add_u32 s48, s48, s58
	s_addc_u32 s49, s49, 0
	s_lshl_b32 s51, s50, 5
	s_lshl_b32 s61, s59, 1
	s_add_u32 s60, s60, s61
	s_add_u32 s52, s44, s60
	s_addc_u32 s53, s45, 0
	v_mad_u32_u24 v207, v201, s50, v200
	global_load_dwordx4 v[216:219], v207, s[48:49] nt
	s_add_u32 s48, s48, s51
	s_addc_u32 s49, s49, 0
	global_load_dwordx4 v[220:223], v207, s[48:49] nt
	s_cmp_eq_u32 s47, 0
	s_cbranch_scc1 .LcvA_w2_0
	s_waitcnt vmcnt(2)
	s_branch .LcvA_go0

.LcvA_ld3_end:
	s_lshl_b32 s55, s55, 6
	s_lshl_b32 s59, s59, 6
	s_mul_i32 s58, s59, s50
	s_lshl_b32 s61, s55, 2
	s_add_u32 s58, s58, s61
	s_add_u32 s48, s48, s58
	s_addc_u32 s49, s49, 0
	s_lshl_b32 s51, s50, 5
	s_lshl_b32 s61, s59, 1
	s_add_u32 s60, s60, s61
	s_add_u32 s52, s44, s60
	s_addc_u32 s53, s45, 0
	v_mad_u32_u24 v207, v201, s50, v200
	global_load_dwordx4 v[208:211], v207, s[48:49] nt
	s_add_u32 s48, s48, s51
	s_addc_u32 s49, s49, 0
	global_load_dwordx4 v[212:215], v207, s[48:49] nt
	s_cmp_eq_u32 s47, 0
	s_cbranch_scc1 .LcvA_w2_1
	s_waitcnt vmcnt(2)
	s_branch .LcvA_go1
